# diff loop max3 chain: removed nine compiler pads (s_nop 0 after inline-asm max3) that guard no hazard; MFMA-result spacing kept at 12 states
# baseline (speedup 1.0000x reference)
.LBB0_481:
	s_or_b64 exec, exec, s[0:1]
	s_nop 7
	v_max3_f32 v170, v82, v66, v83
	v_max3_f32 v170, v170, v67, v84
	v_max3_f32 v170, v170, v68, v85
	v_max3_f32 v170, v170, v69, v86
	v_cndmask_b32_e32 v0, 0, v149, vcc
	v_max3_f32 v170, v170, v70, v87
	s_mov_b32 s0, 0x41200000
	v_max3_f32 v170, v170, v71, v88
	v_max3_f32 v170, v170, v72, v89
	v_max3_f32 v170, v170, v73, v90
	v_max3_f32 v170, v170, v74, v91
	v_max3_f32 v170, v170, v75, v92
	v_max3_f32 v170, v170, v76, v93
	v_max3_f32 v170, v170, v77, v94
	v_max3_f32 v170, v170, v78, v95
	v_max3_f32 v170, v170, v79, v96
	v_max3_f32 v170, v170, v80, v97
	s_nop 0
	v_max_f32_e32 v170, v170, v81
	v_mov_b32_e32 v171, v170
	s_nop 1
	v_permlane32_swap_b32_e32 v171, v170
	v_max_f32_e32 v170, v170, v171
	v_add_f32_e32 v170, v0, v170
	v_sub_f32_e32 v171, v170, v150
	v_cmp_lt_f32_e32 vcc, s0, v171
	s_cbranch_vccnz .Ldf_rescale
